# nine grid barriers (0-4, 6-9) split into arrive / one-round weight-transpose slice / wait; rounds 1..10 of the phase-0 item loop spread over them (deadlines: each weight finished at least one barrier
# speedup vs baseline: 1.0255x; 1.0121x over previous
.LBB0_189:
	s_cmp_lg_u32 s88, 0
	s_cbranch_scc1 .Lsl1_out
	s_cmp_lg_u32 s89, 18
	s_cbranch_scc1 .Lsl1_out
	s_load_dword s4, s[0:1], 0x120
	s_load_dwordx16 s[52:67], s[0:1], 0x0
	s_load_dwordx16 s[68:83], s[0:1], 0x80
	s_waitcnt lgkmcnt(0)
	s_lshl_b32 s4, s4, 1
	s_mul_i32 s5, s4, 3
	s_lshl_b32 s33, s2, 1
	s_add_i32 s33, s33, s5
	s_mov_b32 s5, 4
	s_mul_i32 s4, s4, s5
	s_min_u32 s4, s4, 0x15d0
	s_cmp_ge_i32 s33, s4
	s_cbranch_scc1 .Lsl1_out
	s_add_u32 s94, s34, 0x1da0000
	s_addc_u32 s95, s35, 0
	v_writelane_b32 v252, s90, 0
	s_add_u32 s4, s34, 0x7a0000
	s_addc_u32 s5, s35, 0
	v_writelane_b32 v252, s91, 1
	v_writelane_b32 v252, s4, 2
	v_lshrrev_b32_e32 v138, 8, v204
	v_and_b32_e32 v139, 0xff, v204
	v_writelane_b32 v252, s5, 3
	s_add_u32 s4, s34, 0x720000
	s_addc_u32 s5, s35, 0
	v_writelane_b32 v252, s4, 4
	v_mul_u32_u24_e32 v140, 0x12000, v138
	v_mov_b32_e32 v129, 0
	v_writelane_b32 v252, s5, 5
	s_add_u32 s4, s34, 0x520000
	s_addc_u32 s5, s35, 0
	s_add_u32 s90, s34, 0x4a0000
	s_addc_u32 s91, s35, 0
	s_add_u32 s96, s34, 0x440000
	s_addc_u32 s97, s35, 0
	s_add_u32 s16, s34, 0x28a0000
	s_addc_u32 s17, s35, 0
	s_add_u32 s18, s0, 0x120
	v_writelane_b32 v252, s4, 6
	s_addc_u32 s19, s1, 0
	s_movk_i32 s8, 0x104
	s_movk_i32 s9, 0xffe0
	s_movk_i32 s10, 0x6000
	s_movk_i32 s11, 0x400
	s_mov_b32 s12, 0xbfb8aa3b
	s_mov_b32 s13, 0x42ce8ed0
	s_mov_b32 s14, 0xc2b17218
	s_movk_i32 s15, 0x1800
	v_mov_b32_e32 v141, 0xfffffd40
	v_mov_b32_e32 v142, 0xb00000
	v_mov_b32_e32 v143, 0x580000
	v_mov_b32_e32 v144, 0x7f800000
	v_writelane_b32 v252, s5, 7
	s_branch .Lsl1_22

.Lsl1_21:
	s_or_b64 exec, exec, s[20:21]
	s_waitcnt lgkmcnt(0)
	s_load_dword s4, s[18:19], 0x0
	s_waitcnt lgkmcnt(0)
	s_lshl_b32 s4, s4, 1
	s_add_i32 s33, s4, s33
	s_mov_b32 s5, 4
	s_mul_i32 s4, s4, s5
	s_min_u32 s4, s4, 0x15d0
	s_cmp_lt_i32 s33, s4
	s_cbranch_scc0 .Lsl1_71

.LBB0_480:
	s_cmp_lg_u32 s88, 0
	s_cbranch_scc1 .Lsl2_out
	s_cmp_lg_u32 s89, 18
	s_cbranch_scc1 .Lsl2_out
	s_load_dword s4, s[0:1], 0x120
	s_load_dwordx16 s[52:67], s[0:1], 0x0
	s_load_dwordx16 s[68:83], s[0:1], 0x80
	s_waitcnt lgkmcnt(0)
	s_lshl_b32 s4, s4, 1
	s_mul_i32 s5, s4, 4
	s_lshl_b32 s33, s2, 1
	s_add_i32 s33, s33, s5
	s_mov_b32 s5, 5
	s_mul_i32 s4, s4, s5
	s_min_u32 s4, s4, 0x15d0
	s_cmp_ge_i32 s33, s4
	s_cbranch_scc1 .Lsl2_out
	s_add_u32 s94, s34, 0x1da0000
	s_addc_u32 s95, s35, 0
	v_writelane_b32 v252, s90, 0
	s_add_u32 s4, s34, 0x7a0000
	s_addc_u32 s5, s35, 0
	v_writelane_b32 v252, s91, 1
	v_writelane_b32 v252, s4, 2
	v_lshrrev_b32_e32 v138, 8, v204
	v_and_b32_e32 v139, 0xff, v204
	v_writelane_b32 v252, s5, 3
	s_add_u32 s4, s34, 0x720000
	s_addc_u32 s5, s35, 0
	v_writelane_b32 v252, s4, 4
	v_mul_u32_u24_e32 v140, 0x12000, v138
	v_mov_b32_e32 v129, 0
	v_writelane_b32 v252, s5, 5
	s_add_u32 s4, s34, 0x520000
	s_addc_u32 s5, s35, 0
	s_add_u32 s90, s34, 0x4a0000
	s_addc_u32 s91, s35, 0
	s_add_u32 s96, s34, 0x440000
	s_addc_u32 s97, s35, 0
	s_add_u32 s16, s34, 0x28a0000
	s_addc_u32 s17, s35, 0
	s_add_u32 s18, s0, 0x120
	v_writelane_b32 v252, s4, 6
	s_addc_u32 s19, s1, 0
	s_movk_i32 s8, 0x104
	s_movk_i32 s9, 0xffe0
	s_movk_i32 s10, 0x6000
	s_movk_i32 s11, 0x400
	s_mov_b32 s12, 0xbfb8aa3b
	s_mov_b32 s13, 0x42ce8ed0
	s_mov_b32 s14, 0xc2b17218
	s_movk_i32 s15, 0x1800
	v_mov_b32_e32 v141, 0xfffffd40
	v_mov_b32_e32 v142, 0xb00000
	v_mov_b32_e32 v143, 0x580000
	v_mov_b32_e32 v144, 0x7f800000
	v_writelane_b32 v252, s5, 7
	s_branch .Lsl2_22

.LBB0_615:
	s_cmp_lg_u32 s88, 0
	s_cbranch_scc1 .Lsl3_out
	s_cmp_lg_u32 s89, 18
	s_cbranch_scc1 .Lsl3_out
	s_load_dword s4, s[0:1], 0x120
	s_load_dwordx16 s[52:67], s[0:1], 0x0
	s_load_dwordx16 s[68:83], s[0:1], 0x80
	s_waitcnt lgkmcnt(0)
	s_lshl_b32 s4, s4, 1
	s_mul_i32 s5, s4, 5
	s_lshl_b32 s33, s2, 1
	s_add_i32 s33, s33, s5
	s_mov_b32 s5, 6
	s_mul_i32 s4, s4, s5
	s_min_u32 s4, s4, 0x15d0
	s_cmp_ge_i32 s33, s4
	s_cbranch_scc1 .Lsl3_out
	s_add_u32 s94, s34, 0x1da0000
	s_addc_u32 s95, s35, 0
	v_writelane_b32 v252, s90, 0
	s_add_u32 s4, s34, 0x7a0000
	s_addc_u32 s5, s35, 0
	v_writelane_b32 v252, s91, 1
	v_writelane_b32 v252, s4, 2
	v_lshrrev_b32_e32 v138, 8, v204
	v_and_b32_e32 v139, 0xff, v204
	v_writelane_b32 v252, s5, 3
	s_add_u32 s4, s34, 0x720000
	s_addc_u32 s5, s35, 0
	v_writelane_b32 v252, s4, 4
	v_mul_u32_u24_e32 v140, 0x12000, v138
	v_mov_b32_e32 v129, 0
	v_writelane_b32 v252, s5, 5
	s_add_u32 s4, s34, 0x520000
	s_addc_u32 s5, s35, 0
	s_add_u32 s90, s34, 0x4a0000
	s_addc_u32 s91, s35, 0
	s_add_u32 s96, s34, 0x440000
	s_addc_u32 s97, s35, 0
	s_add_u32 s16, s34, 0x28a0000
	s_addc_u32 s17, s35, 0
	s_add_u32 s18, s0, 0x120
	v_writelane_b32 v252, s4, 6
	s_addc_u32 s19, s1, 0
	s_movk_i32 s8, 0x104
	s_movk_i32 s9, 0xffe0
	s_movk_i32 s10, 0x6000
	s_movk_i32 s11, 0x400
	s_mov_b32 s12, 0xbfb8aa3b
	s_mov_b32 s13, 0x42ce8ed0
	s_mov_b32 s14, 0xc2b17218
	s_movk_i32 s15, 0x1800
	v_mov_b32_e32 v141, 0xfffffd40
	v_mov_b32_e32 v142, 0xb00000
	v_mov_b32_e32 v143, 0x580000
	v_mov_b32_e32 v144, 0x7f800000
	v_writelane_b32 v252, s5, 7
	s_branch .Lsl3_22

.Lsl3_21:
	s_or_b64 exec, exec, s[20:21]
	s_waitcnt lgkmcnt(0)
	s_load_dword s4, s[18:19], 0x0
	s_waitcnt lgkmcnt(0)
	s_lshl_b32 s4, s4, 1
	s_add_i32 s33, s4, s33
	s_mov_b32 s5, 6
	s_mul_i32 s4, s4, s5
	s_min_u32 s4, s4, 0x15d0
	s_cmp_lt_i32 s33, s4
	s_cbranch_scc0 .Lsl3_71

.LBB0_844:
	s_cmp_lg_u32 s88, 0
	s_cbranch_scc1 .Lsl4_out
	s_cmp_lg_u32 s89, 18
	s_cbranch_scc1 .Lsl4_out
	s_load_dword s4, s[0:1], 0x120
	s_load_dwordx16 s[52:67], s[0:1], 0x0
	s_load_dwordx16 s[68:83], s[0:1], 0x80
	s_waitcnt lgkmcnt(0)
	s_lshl_b32 s4, s4, 1
	s_mul_i32 s5, s4, 6
	s_lshl_b32 s33, s2, 1
	s_add_i32 s33, s33, s5
	s_mov_b32 s5, 7
	s_mul_i32 s4, s4, s5
	s_min_u32 s4, s4, 0x15d0
	s_cmp_ge_i32 s33, s4
	s_cbranch_scc1 .Lsl4_out
	s_add_u32 s94, s34, 0x1da0000
	s_addc_u32 s95, s35, 0
	v_writelane_b32 v252, s90, 0
	s_add_u32 s4, s34, 0x7a0000
	s_addc_u32 s5, s35, 0
	v_writelane_b32 v252, s91, 1
	v_writelane_b32 v252, s4, 2
	v_lshrrev_b32_e32 v138, 8, v204
	v_and_b32_e32 v139, 0xff, v204
	v_writelane_b32 v252, s5, 3
	s_add_u32 s4, s34, 0x720000
	s_addc_u32 s5, s35, 0
	v_writelane_b32 v252, s4, 4
	v_mul_u32_u24_e32 v140, 0x12000, v138
	v_mov_b32_e32 v129, 0
	v_writelane_b32 v252, s5, 5
	s_add_u32 s4, s34, 0x520000
	s_addc_u32 s5, s35, 0
	s_add_u32 s90, s34, 0x4a0000
	s_addc_u32 s91, s35, 0
	s_add_u32 s96, s34, 0x440000
	s_addc_u32 s97, s35, 0
	s_add_u32 s16, s34, 0x28a0000
	s_addc_u32 s17, s35, 0
	s_add_u32 s18, s0, 0x120
	v_writelane_b32 v252, s4, 6
	s_addc_u32 s19, s1, 0
	s_movk_i32 s8, 0x104
	s_movk_i32 s9, 0xffe0
	s_movk_i32 s10, 0x6000
	s_movk_i32 s11, 0x400
	s_mov_b32 s12, 0xbfb8aa3b
	s_mov_b32 s13, 0x42ce8ed0
	s_mov_b32 s14, 0xc2b17218
	s_movk_i32 s15, 0x1800
	v_mov_b32_e32 v141, 0xfffffd40
	v_mov_b32_e32 v142, 0xb00000
	v_mov_b32_e32 v143, 0x580000
	v_mov_b32_e32 v144, 0x7f800000
	v_writelane_b32 v252, s5, 7
	s_branch .Lsl4_22

.LBB0_1014:
	s_cmp_lg_u32 s88, 0
	s_cbranch_scc1 .Lsl6_out
	s_cmp_lg_u32 s89, 18
	s_cbranch_scc1 .Lsl6_out
	s_load_dword s4, s[0:1], 0x120
	s_load_dwordx16 s[52:67], s[0:1], 0x0
	s_load_dwordx16 s[68:83], s[0:1], 0x80
	s_waitcnt lgkmcnt(0)
	s_lshl_b32 s4, s4, 1
	s_mul_i32 s5, s4, 7
	s_lshl_b32 s33, s2, 1
	s_add_i32 s33, s33, s5
	s_mov_b32 s5, 8
	s_mul_i32 s4, s4, s5
	s_min_u32 s4, s4, 0x15d0
	s_cmp_ge_i32 s33, s4
	s_cbranch_scc1 .Lsl6_out
	s_add_u32 s94, s34, 0x1da0000
	s_addc_u32 s95, s35, 0
	v_writelane_b32 v252, s90, 0
	s_add_u32 s4, s34, 0x7a0000
	s_addc_u32 s5, s35, 0
	v_writelane_b32 v252, s91, 1
	v_writelane_b32 v252, s4, 2
	v_lshrrev_b32_e32 v138, 8, v204
	v_and_b32_e32 v139, 0xff, v204
	v_writelane_b32 v252, s5, 3
	s_add_u32 s4, s34, 0x720000
	s_addc_u32 s5, s35, 0
	v_writelane_b32 v252, s4, 4
	v_mul_u32_u24_e32 v140, 0x12000, v138
	v_mov_b32_e32 v129, 0
	v_writelane_b32 v252, s5, 5
	s_add_u32 s4, s34, 0x520000
	s_addc_u32 s5, s35, 0
	s_add_u32 s90, s34, 0x4a0000
	s_addc_u32 s91, s35, 0
	s_add_u32 s96, s34, 0x440000
	s_addc_u32 s97, s35, 0
	s_add_u32 s16, s34, 0x28a0000
	s_addc_u32 s17, s35, 0
	s_add_u32 s18, s0, 0x120
	v_writelane_b32 v252, s4, 6
	s_addc_u32 s19, s1, 0
	s_movk_i32 s8, 0x104
	s_movk_i32 s9, 0xffe0
	s_movk_i32 s10, 0x6000
	s_movk_i32 s11, 0x400
	s_mov_b32 s12, 0xbfb8aa3b
	s_mov_b32 s13, 0x42ce8ed0
	s_mov_b32 s14, 0xc2b17218
	s_movk_i32 s15, 0x1800
	v_mov_b32_e32 v141, 0xfffffd40
	v_mov_b32_e32 v142, 0xb00000
	v_mov_b32_e32 v143, 0x580000
	v_mov_b32_e32 v144, 0x7f800000
	v_writelane_b32 v252, s5, 7
	s_branch .Lsl6_22

.Lsl6_21:
	s_or_b64 exec, exec, s[20:21]
	s_waitcnt lgkmcnt(0)
	s_load_dword s4, s[18:19], 0x0
	s_waitcnt lgkmcnt(0)
	s_lshl_b32 s4, s4, 1
	s_add_i32 s33, s4, s33
	s_mov_b32 s5, 8
	s_mul_i32 s4, s4, s5
	s_min_u32 s4, s4, 0x15d0
	s_cmp_lt_i32 s33, s4
	s_cbranch_scc0 .Lsl6_71

.Lsl6_out:
	s_cmp_gt_i32 s88, 6
	s_cbranch_scc1 .Lsb6_skip
	s_cmp_lt_i32 s89, 8
	s_cbranch_scc1 .Lsb6_skip
	s_waitcnt vmcnt(0) lgkmcnt(0)
	s_and_saveexec_b64 s[16:17], s[92:93]
	s_cbranch_execz .Lsb6_done
	v_mov_b32_e32 v0, 0x24008
	ds_read_b32 v1, v0
	buffer_inv sc1
	s_add_u32 s18, s34, 0xed10500
	s_addc_u32 s19, s35, 0
	v_mov_b32_e32 v0, 0
	s_mov_b32 s20, 0
	s_waitcnt lgkmcnt(0)

.Lsb6_skip:
	s_cmp_gt_i32 s89, 7
	s_cselect_b64 s[6:7], -1, 0
	s_waitcnt lgkmcnt(0)
	s_cmp_lt_i32 s88, 8
	s_cselect_b64 s[4:5], -1, 0
	s_and_b64 s[6:7], s[4:5], s[6:7]
	s_andn2_b64 vcc, exec, s[6:7]
	s_cbranch_vccnz .LBB0_1023
	s_cmpk_gt_i32 s2, 0xff
	s_cbranch_scc1 .LBB0_1023
	s_load_dword s9, s[0:1], 0x120
	v_readfirstlane_b32 s42, v205
	v_and_b32_e32 v192, 15, v204
	v_bfe_u32 v193, v204, 4, 2
	v_lshrrev_b32_e32 v194, 8, v204
	v_bfe_u32 v195, v204, 6, 2
	v_bfe_u32 v196, v204, 1, 3
	v_xor_b32_e32 v197, v193, v196
	v_xor_b32_e32 v198, 4, v197
	v_lshlrev_b32_e32 v197, 4, v197
	v_lshlrev_b32_e32 v198, 4, v198
	v_lshlrev_b32_e32 v199, 14, v194
	v_lshl_add_u32 v199, v192, 7, v199
	v_add_u32_e32 v242, v199, v197
	v_add_u32_e32 v243, v199, v198
	v_lshlrev_b32_e32 v199, 13, v195
	v_lshl_add_u32 v199, v192, 7, v199
	v_add_u32_e32 v199, 0x8000, v199
	v_add_u32_e32 v244, v199, v197
	v_add_u32_e32 v245, v199, v198
	v_add_u32_e32 v246, 0x10000, v242
	v_add_u32_e32 v248, 0x10000, v244
	v_add_u32_e32 v247, 0x10000, v243
	v_add_u32_e32 v249, 0x10000, v245
	v_lshrrev_b32_e32 v199, 3, v204
	v_and_b32_e32 v200, 7, v204
	v_bfe_u32 v201, v204, 4, 3
	v_xor_b32_e32 v200, v200, v201
	v_lshlrev_b32_e32 v200, 4, v200
	v_lshl_add_u32 v238, v199, 11, v200
	v_add_u32_e32 v239, 0x20000, v238
	v_add_u32_e32 v240, 0x40000, v238
	v_add_u32_e32 v241, 0x60000, v238
	s_lshl_b32 s42, s42, 10
	s_mov_b32 s8, s2
	s_and_b32 s44, s8, 7
	s_lshl_b32 s44, s44, 5
	s_lshr_b32 s45, s8, 3
	s_add_i32 s44, s44, s45
	s_lshr_b32 s45, s44, 7
	s_and_b32 s44, s44, 127
	s_and_b32 s98, s44, 3
	s_lshl_b32 s15, s98, 8
	s_lshr_b32 s44, s44, 2
	s_lshl_b32 s14, s44, 8
	s_mul_i32 s44, s14, 0x800
	s_mul_i32 s98, s45, 0x400
	s_add_u32 s44, s44, s98
	s_add_u32 s44, s44, 0x9a44000
	s_add_u32 s10, s34, s44
	s_addc_u32 s11, s35, 0
	s_mul_i32 s44, s15, 0x800
	s_add_u32 s44, s44, s98
	s_add_u32 s44, s44, 0x520000
	s_add_u32 s12, s34, s44
	s_addc_u32 s13, s35, 0
	s_lshl_b32 s45, s45, 16
	s_or_b32 s14, s14, s45
	s_waitcnt vmcnt(0) lgkmcnt(0)
	s_barrier
	s_add_u32 m0, s42, 0x0
	s_nop 0
	global_load_lds_dwordx4 v238, s[10:11]
	s_add_u32 m0, s42, 0x2000
	s_nop 0
	global_load_lds_dwordx4 v239, s[10:11]
	s_add_u32 m0, s42, 0x4000
	s_nop 0
	global_load_lds_dwordx4 v240, s[10:11]
	s_add_u32 m0, s42, 0x6000
	s_nop 0
	global_load_lds_dwordx4 v241, s[10:11]
	s_add_u32 m0, s42, 0x8000
	s_nop 0
	global_load_lds_dwordx4 v238, s[12:13]
	s_add_u32 m0, s42, 0xa000
	s_nop 0
	global_load_lds_dwordx4 v239, s[12:13]
	s_add_u32 m0, s42, 0xc000
	s_nop 0
	global_load_lds_dwordx4 v240, s[12:13]
	s_add_u32 m0, s42, 0xe000
	s_nop 0
	global_load_lds_dwordx4 v241, s[12:13]
	s_waitcnt vmcnt(0)

.LBB0_1077:
	s_cmp_lg_u32 s88, 0
	s_cbranch_scc1 .Lsl7_out
	s_cmp_lg_u32 s89, 18
	s_cbranch_scc1 .Lsl7_out
	s_load_dword s4, s[0:1], 0x120
	s_load_dwordx16 s[52:67], s[0:1], 0x0
	s_load_dwordx16 s[68:83], s[0:1], 0x80
	s_waitcnt lgkmcnt(0)
	s_lshl_b32 s4, s4, 1
	s_mul_i32 s5, s4, 8
	s_lshl_b32 s33, s2, 1
	s_add_i32 s33, s33, s5
	s_mov_b32 s5, 9
	s_mul_i32 s4, s4, s5
	s_min_u32 s4, s4, 0x15d0
	s_cmp_ge_i32 s33, s4
	s_cbranch_scc1 .Lsl7_out
	s_add_u32 s94, s34, 0x1da0000
	s_addc_u32 s95, s35, 0
	v_writelane_b32 v252, s90, 0
	s_add_u32 s4, s34, 0x7a0000
	s_addc_u32 s5, s35, 0
	v_writelane_b32 v252, s91, 1
	v_writelane_b32 v252, s4, 2
	v_lshrrev_b32_e32 v138, 8, v204
	v_and_b32_e32 v139, 0xff, v204
	v_writelane_b32 v252, s5, 3
	s_add_u32 s4, s34, 0x720000
	s_addc_u32 s5, s35, 0
	v_writelane_b32 v252, s4, 4
	v_mul_u32_u24_e32 v140, 0x12000, v138
	v_mov_b32_e32 v129, 0
	v_writelane_b32 v252, s5, 5
	s_add_u32 s4, s34, 0x520000
	s_addc_u32 s5, s35, 0
	s_add_u32 s90, s34, 0x4a0000
	s_addc_u32 s91, s35, 0
	s_add_u32 s96, s34, 0x440000
	s_addc_u32 s97, s35, 0
	s_add_u32 s16, s34, 0x28a0000
	s_addc_u32 s17, s35, 0
	s_add_u32 s18, s0, 0x120
	v_writelane_b32 v252, s4, 6
	s_addc_u32 s19, s1, 0
	s_movk_i32 s8, 0x104
	s_movk_i32 s9, 0xffe0
	s_movk_i32 s10, 0x6000
	s_movk_i32 s11, 0x400
	s_mov_b32 s12, 0xbfb8aa3b
	s_mov_b32 s13, 0x42ce8ed0
	s_mov_b32 s14, 0xc2b17218
	s_movk_i32 s15, 0x1800
	v_mov_b32_e32 v141, 0xfffffd40
	v_mov_b32_e32 v142, 0xb00000
	v_mov_b32_e32 v143, 0x580000
	v_mov_b32_e32 v144, 0x7f800000
	v_writelane_b32 v252, s5, 7
	s_branch .Lsl7_22

.Lsl7_out:
	s_cmp_gt_i32 s88, 7
	s_cbranch_scc1 .Lsb7_skip
	s_cmp_lt_i32 s89, 9
	s_cbranch_scc1 .Lsb7_skip
	s_waitcnt vmcnt(0) lgkmcnt(0)
	s_and_saveexec_b64 s[16:17], s[92:93]
	s_cbranch_execz .Lsb7_done
	v_mov_b32_e32 v0, 0x24008
	ds_read_b32 v1, v0
	buffer_inv sc1
	s_add_u32 s18, s34, 0xed10500
	s_addc_u32 s19, s35, 0
	v_mov_b32_e32 v0, 0
	s_mov_b32 s20, 0
	s_waitcnt lgkmcnt(0)

.Lsb7_skip:
	s_cmp_gt_i32 s89, 8
	s_cselect_b64 s[6:7], -1, 0
	s_waitcnt lgkmcnt(0)
	s_cmp_lt_i32 s88, 9
	s_cselect_b64 s[8:9], -1, 0
	s_and_b64 s[4:5], s[8:9], s[6:7]
	s_andn2_b64 vcc, exec, s[4:5]
	s_cbranch_vccnz .LBB0_1086
	s_waitcnt vmcnt(7)
	v_lshl_add_u32 v0, s2, 3, v205
	s_movk_i32 s4, 0x2000
	v_cmp_gt_i32_e32 vcc, s4, v0
	s_and_saveexec_b64 s[6:7], vcc
	s_cbranch_execz .LBB0_1085
	v_lshlrev_b32_e32 v1, 2, v204
	s_waitcnt vmcnt(3)
	v_and_b32_e32 v16, 0xfc, v1
	v_mbcnt_lo_u32_b32 v1, -1, 0
	v_mov_b32_e32 v3, 0
	v_lshlrev_b32_e32 v2, 1, v16
	v_mbcnt_hi_u32_b32 v1, -1, v1
	v_lshl_add_u64 v[14:15], s[34:35], 0, v[2:3]
	v_and_b32_e32 v2, 64, v1
	v_add_u32_e32 v2, 64, v2
	v_xor_b32_e32 v8, 32, v1
	v_cmp_lt_i32_e32 vcc, v8, v2
	s_mov_b64 s[4:5], 0x28c4000
	v_lshl_add_u64 v[4:5], v[14:15], 0, s[4:5]
	v_cndmask_b32_e32 v8, v1, v8, vcc
	s_waitcnt vmcnt(0)
	v_lshlrev_b32_e32 v28, 2, v8
	v_xor_b32_e32 v8, 16, v1
	v_cmp_lt_i32_e32 vcc, v8, v2
	s_mov_b64 s[4:5], 0x38c4000
	s_load_dwordx16 s[16:31], s[0:1], 0x40
	v_cndmask_b32_e32 v8, v1, v8, vcc
	v_lshlrev_b32_e32 v29, 2, v8
	v_xor_b32_e32 v8, 8, v1
	v_cmp_lt_i32_e32 vcc, v8, v2
	v_lshl_add_u64 v[6:7], v[14:15], 0, s[4:5]
	s_load_dword s4, s[0:1], 0x120
	v_cndmask_b32_e32 v8, v1, v8, vcc
	v_lshlrev_b32_e32 v30, 2, v8
	v_xor_b32_e32 v8, 4, v1
	v_cmp_lt_i32_e32 vcc, v8, v2
	s_add_u32 s10, s34, 0x28a0000
	s_waitcnt lgkmcnt(0)
	s_mov_b64 s[16:17], s[20:21]
	v_cndmask_b32_e32 v8, v1, v8, vcc
	v_lshlrev_b32_e32 v31, 2, v8
	v_xor_b32_e32 v8, 2, v1
	v_cmp_lt_i32_e32 vcc, v8, v2
	s_addc_u32 s11, s35, 0
	s_lshl_b32 s14, s4, 3
	v_cndmask_b32_e32 v8, v1, v8, vcc
	v_lshlrev_b32_e32 v32, 2, v8
	v_xor_b32_e32 v8, 1, v1
	v_cmp_lt_i32_e32 vcc, v8, v2
	v_lshlrev_b32_e32 v2, 2, v16
	s_mov_b64 s[18:19], s[22:23]
	s_mov_b64 s[20:21], s[24:25]
	s_mov_b64 s[4:5], 0xed11000
	v_cndmask_b32_e32 v1, v1, v8, vcc
	s_mov_b64 s[22:23], s[26:27]
	v_lshl_add_u64 v[8:9], s[20:21], 0, v[2:3]
	v_lshl_add_u64 v[10:11], s[18:19], 0, v[2:3]
	v_or_b32_e32 v2, 0x100, v16
	v_or_b32_e32 v20, 0x200, v16
	v_or_b32_e32 v22, 0x300, v16
	v_lshl_add_u64 v[12:13], v[14:15], 0, s[4:5]
	s_mov_b64 s[4:5], 0x8a44000
	v_lshlrev_b32_e32 v33, 2, v1
	v_lshl_add_u64 v[14:15], v[14:15], 0, s[4:5]
	s_mov_b64 s[12:13], 0
	s_movk_i32 s15, 0x1000
	s_movk_i32 s22, 0xfff
	s_movk_i32 s23, 0x1800
	v_lshlrev_b32_e32 v16, 2, v16
	v_mov_b32_e32 v17, v3
	s_mov_b64 s[16:17], 0x2000
	v_lshlrev_b32_e32 v18, 2, v2
	v_mov_b32_e32 v19, v3
	v_lshlrev_b32_e32 v20, 2, v20
	v_mov_b32_e32 v21, v3
	v_lshlrev_b32_e32 v22, 2, v22
	v_mov_b32_e32 v23, v3
	v_mov_b32_e32 v34, 0x358637bd
	s_mov_b32 s24, 0x800000
	s_mov_b64 s[18:19], 0x3000
	s_mov_b64 s[20:21], 0x4000
	s_movk_i32 s25, 0x1fff
	s_branch .LBB0_1081

.LBB0_1140:
	s_cmp_lg_u32 s88, 0
	s_cbranch_scc1 .Lsl8_out
	s_cmp_lg_u32 s89, 18
	s_cbranch_scc1 .Lsl8_out
	s_load_dword s4, s[0:1], 0x120
	s_load_dwordx16 s[52:67], s[0:1], 0x0
	s_load_dwordx16 s[68:83], s[0:1], 0x80
	s_waitcnt lgkmcnt(0)
	s_lshl_b32 s4, s4, 1
	s_mul_i32 s5, s4, 9
	s_lshl_b32 s33, s2, 1
	s_add_i32 s33, s33, s5
	s_mov_b32 s5, 10
	s_mul_i32 s4, s4, s5
	s_min_u32 s4, s4, 0x15d0
	s_cmp_ge_i32 s33, s4
	s_cbranch_scc1 .Lsl8_out
	s_add_u32 s94, s34, 0x1da0000
	s_addc_u32 s95, s35, 0
	v_writelane_b32 v252, s90, 0
	s_add_u32 s4, s34, 0x7a0000
	s_addc_u32 s5, s35, 0
	v_writelane_b32 v252, s91, 1
	v_writelane_b32 v252, s4, 2
	v_lshrrev_b32_e32 v138, 8, v204
	v_and_b32_e32 v139, 0xff, v204
	v_writelane_b32 v252, s5, 3
	s_add_u32 s4, s34, 0x720000
	s_addc_u32 s5, s35, 0
	v_writelane_b32 v252, s4, 4
	v_mul_u32_u24_e32 v140, 0x12000, v138
	v_mov_b32_e32 v129, 0
	v_writelane_b32 v252, s5, 5
	s_add_u32 s4, s34, 0x520000
	s_addc_u32 s5, s35, 0
	s_add_u32 s90, s34, 0x4a0000
	s_addc_u32 s91, s35, 0
	s_add_u32 s96, s34, 0x440000
	s_addc_u32 s97, s35, 0
	s_add_u32 s16, s34, 0x28a0000
	s_addc_u32 s17, s35, 0
	s_add_u32 s18, s0, 0x120
	v_writelane_b32 v252, s4, 6
	s_addc_u32 s19, s1, 0
	s_movk_i32 s8, 0x104
	s_movk_i32 s9, 0xffe0
	s_movk_i32 s10, 0x6000
	s_movk_i32 s11, 0x400
	s_mov_b32 s12, 0xbfb8aa3b
	s_mov_b32 s13, 0x42ce8ed0
	s_mov_b32 s14, 0xc2b17218
	s_movk_i32 s15, 0x1800
	v_mov_b32_e32 v141, 0xfffffd40
	v_mov_b32_e32 v142, 0xb00000
	v_mov_b32_e32 v143, 0x580000
	v_mov_b32_e32 v144, 0x7f800000
	v_writelane_b32 v252, s5, 7
	s_branch .Lsl8_22

.Lsl8_21:
	s_or_b64 exec, exec, s[20:21]
	s_waitcnt lgkmcnt(0)
	s_load_dword s4, s[18:19], 0x0
	s_waitcnt lgkmcnt(0)
	s_lshl_b32 s4, s4, 1
	s_add_i32 s33, s4, s33
	s_mov_b32 s5, 10
	s_mul_i32 s4, s4, s5
	s_min_u32 s4, s4, 0x15d0
	s_cmp_lt_i32 s33, s4
	s_cbranch_scc0 .Lsl8_71

.Lsl8_out:
	s_cmp_gt_i32 s88, 8
	s_cbranch_scc1 .Lsb8_skip
	s_cmp_lt_i32 s89, 10
	s_cbranch_scc1 .Lsb8_skip
	s_waitcnt vmcnt(0) lgkmcnt(0)
	s_and_saveexec_b64 s[16:17], s[92:93]
	s_cbranch_execz .Lsb8_done
	v_mov_b32_e32 v0, 0x24008
	ds_read_b32 v1, v0
	buffer_inv sc1
	s_add_u32 s18, s34, 0xed10500
	s_addc_u32 s19, s35, 0
	v_mov_b32_e32 v0, 0
	s_mov_b32 s20, 0
	s_waitcnt lgkmcnt(0)

.Lsb8_skip:
	s_cmp_gt_i32 s89, 9
	s_cselect_b64 s[4:5], -1, 0
	s_waitcnt lgkmcnt(0)
	s_cmp_lt_i32 s88, 10
	s_cselect_b64 s[6:7], -1, 0
	s_and_b64 s[4:5], s[6:7], s[4:5]
	s_andn2_b64 vcc, exec, s[4:5]
	s_cbranch_vccnz .LBB0_1148
	s_cmpk_gt_i32 s2, 0x2bf
	s_cbranch_scc1 .LBB0_1148
	s_load_dword s9, s[0:1], 0x120
	v_readfirstlane_b32 s42, v205
	v_and_b32_e32 v192, 15, v204
	v_bfe_u32 v193, v204, 4, 2
	v_lshrrev_b32_e32 v194, 8, v204
	v_bfe_u32 v195, v204, 6, 2
	v_bfe_u32 v196, v204, 1, 3
	v_xor_b32_e32 v197, v193, v196
	v_xor_b32_e32 v198, 4, v197
	v_lshlrev_b32_e32 v197, 4, v197
	v_lshlrev_b32_e32 v198, 4, v198
	v_lshlrev_b32_e32 v199, 14, v194
	v_lshl_add_u32 v199, v192, 7, v199
	v_add_u32_e32 v242, v199, v197
	v_add_u32_e32 v243, v199, v198
	v_lshlrev_b32_e32 v199, 13, v195
	v_lshl_add_u32 v199, v192, 7, v199
	v_add_u32_e32 v199, 0x8000, v199
	v_add_u32_e32 v244, v199, v197
	v_add_u32_e32 v245, v199, v198
	v_add_u32_e32 v246, 0x10000, v242
	v_add_u32_e32 v248, 0x10000, v244
	v_add_u32_e32 v247, 0x10000, v243
	v_add_u32_e32 v249, 0x10000, v245
	v_lshrrev_b32_e32 v199, 3, v204
	v_and_b32_e32 v200, 7, v204
	v_bfe_u32 v201, v204, 4, 3
	v_xor_b32_e32 v200, v200, v201
	v_lshlrev_b32_e32 v200, 4, v200
	v_lshl_add_u32 v238, v199, 11, v200
	v_add_u32_e32 v239, 0x20000, v238
	v_add_u32_e32 v240, 0x40000, v238
	v_add_u32_e32 v241, 0x60000, v238
	s_lshl_b32 s42, s42, 10
	s_mov_b32 s8, s2
	s_and_b32 s44, s8, 7
	s_mulk_i32 s44, 0x58
	s_lshr_b32 s45, s8, 3
	s_add_i32 s44, s44, s45
	s_cmpk_ge_i32 s44, 176
	s_cselect_b32 s45, 1, 0
	s_cmpk_ge_i32 s44, 352
	s_cselect_b32 s98, 1, 0
	s_add_i32 s45, s45, s98
	s_cmpk_ge_i32 s44, 528
	s_cselect_b32 s98, 1, 0
	s_add_i32 s45, s45, s98
	s_mul_i32 s98, s45, 176
	s_sub_i32 s44, s44, s98
	s_and_b32 s98, s44, 7
	s_lshl_b32 s45, s45, 3
	s_add_i32 s45, s45, s98
	s_lshl_b32 s14, s45, 8
	s_lshr_b32 s44, s44, 3
	s_lshl_b32 s15, s44, 8
	s_mul_i32 s44, s14, 0x800
	s_add_u32 s44, s44, 0x8a44000
	s_add_u32 s10, s34, s44
	s_addc_u32 s11, s35, 0
	s_mul_i32 s44, s15, 0x800
	s_add_u32 s44, s44, 0x7a0000
	s_add_u32 s12, s34, s44
	s_addc_u32 s13, s35, 0
	s_waitcnt vmcnt(0) lgkmcnt(0)
	s_barrier
	s_add_u32 m0, s42, 0x0
	s_nop 0
	global_load_lds_dwordx4 v238, s[10:11]
	s_add_u32 m0, s42, 0x2000
	s_nop 0
	global_load_lds_dwordx4 v239, s[10:11]
	s_add_u32 m0, s42, 0x4000
	s_nop 0
	global_load_lds_dwordx4 v240, s[10:11]
	s_add_u32 m0, s42, 0x6000
	s_nop 0
	global_load_lds_dwordx4 v241, s[10:11]
	s_add_u32 m0, s42, 0x8000
	s_nop 0
	global_load_lds_dwordx4 v238, s[12:13]
	s_add_u32 m0, s42, 0xa000
	s_nop 0
	global_load_lds_dwordx4 v239, s[12:13]
	s_add_u32 m0, s42, 0xc000
	s_nop 0
	global_load_lds_dwordx4 v240, s[12:13]
	s_add_u32 m0, s42, 0xe000
	s_nop 0
	global_load_lds_dwordx4 v241, s[12:13]
	s_waitcnt vmcnt(0)

.LBB0_1165:
	s_mov_b64 s[10:11], exec
	s_lshl_b32 s6, s3, 8
	v_mbcnt_lo_u32_b32 v1, s10, 0
	s_add_u32 s6, s90, s6
	v_mbcnt_hi_u32_b32 v1, s11, v1
	s_addc_u32 s7, s91, 0
	v_cmp_eq_u32_e32 vcc, 0, v1
	s_and_saveexec_b64 s[12:13], vcc
	s_cbranch_execz .LBB0_1167
	s_bcnt1_i32_b64 s10, s[10:11]
	v_mov_b32_e32 v3, 0x1000
	v_mov_b32_e32 v4, s10
	global_atomic_add v3, v3, v4, s[6:7] offset:1024 sc0
.LBB0_1167:
	s_or_b64 exec, exec, s[12:13]
	v_cvt_f32_u32_e32 v4, v2
	s_waitcnt vmcnt(0)
	v_readfirstlane_b32 s10, v3
	v_sub_u32_e32 v3, 0, v2
	v_rcp_iflag_f32_e32 v4, v4
	v_add_u32_e32 v5, s10, v1
	v_mul_f32_e32 v4, 0x4f7ffffe, v4
	v_cvt_u32_f32_e32 v4, v4
	v_mul_lo_u32 v1, v3, v4
	v_mul_hi_u32 v1, v4, v1
	v_add_u32_e32 v1, v4, v1
	v_mul_hi_u32 v1, v5, v1
	v_mul_lo_u32 v3, v1, v2
	v_sub_u32_e32 v3, v5, v3
	v_add_u32_e32 v4, 1, v1
	v_cmp_ge_u32_e32 vcc, v3, v2
	s_nop 1
	v_cndmask_b32_e32 v1, v1, v4, vcc
	v_sub_u32_e32 v4, v3, v2
	v_cndmask_b32_e32 v3, v3, v4, vcc
	v_add_u32_e32 v4, 1, v1
	v_cmp_ge_u32_e32 vcc, v3, v2
	v_add_u32_e32 v3, 1, v5
	s_nop 0
	v_cndmask_b32_e32 v1, v1, v4, vcc
	v_mul_lo_u32 v4, v2, v1
	v_add_u32_e32 v2, v4, v2
	v_cmp_ne_u32_e32 vcc, v3, v2
	s_and_saveexec_b64 s[10:11], vcc
	s_xor_b64 s[10:11], exec, s[10:11]
	s_cbranch_execz .LBB0_1181
	s_waitcnt lgkmcnt(0)
	v_mov_b32_e32 v0, 0x24008
	ds_write_b32 v0, v1
	s_waitcnt vmcnt(0)
	s_waitcnt vmcnt(0)

.LBB0_1202:
	s_cmp_lg_u32 s88, 0
	s_cbranch_scc1 .Lsl9_out
	s_cmp_lg_u32 s89, 18
	s_cbranch_scc1 .Lsl9_out
	s_load_dword s4, s[0:1], 0x120
	s_load_dwordx16 s[52:67], s[0:1], 0x0
	s_load_dwordx16 s[68:83], s[0:1], 0x80
	s_waitcnt lgkmcnt(0)
	s_lshl_b32 s4, s4, 1
	s_mul_i32 s5, s4, 10
	s_lshl_b32 s33, s2, 1
	s_add_i32 s33, s33, s5
	s_mov_b32 s5, 11
	s_mul_i32 s4, s4, s5
	s_min_u32 s4, s4, 0x15d0
	s_cmp_ge_i32 s33, s4
	s_cbranch_scc1 .Lsl9_out
	s_add_u32 s94, s34, 0x1da0000
	s_addc_u32 s95, s35, 0
	v_writelane_b32 v252, s90, 0
	s_add_u32 s4, s34, 0x7a0000
	s_addc_u32 s5, s35, 0
	v_writelane_b32 v252, s91, 1
	v_writelane_b32 v252, s4, 2
	v_lshrrev_b32_e32 v138, 8, v204
	v_and_b32_e32 v139, 0xff, v204
	v_writelane_b32 v252, s5, 3
	s_add_u32 s4, s34, 0x720000
	s_addc_u32 s5, s35, 0
	v_writelane_b32 v252, s4, 4
	v_mul_u32_u24_e32 v140, 0x12000, v138
	v_mov_b32_e32 v129, 0
	v_writelane_b32 v252, s5, 5
	s_add_u32 s4, s34, 0x520000
	s_addc_u32 s5, s35, 0
	s_add_u32 s90, s34, 0x4a0000
	s_addc_u32 s91, s35, 0
	s_add_u32 s96, s34, 0x440000
	s_addc_u32 s97, s35, 0
	s_add_u32 s16, s34, 0x28a0000
	s_addc_u32 s17, s35, 0
	s_add_u32 s18, s0, 0x120
	v_writelane_b32 v252, s4, 6
	s_addc_u32 s19, s1, 0
	s_movk_i32 s8, 0x104
	s_movk_i32 s9, 0xffe0
	s_movk_i32 s10, 0x6000
	s_movk_i32 s11, 0x400
	s_mov_b32 s12, 0xbfb8aa3b
	s_mov_b32 s13, 0x42ce8ed0
	s_mov_b32 s14, 0xc2b17218
	s_movk_i32 s15, 0x1800
	v_mov_b32_e32 v141, 0xfffffd40
	v_mov_b32_e32 v142, 0xb00000
	v_mov_b32_e32 v143, 0x580000
	v_mov_b32_e32 v144, 0x7f800000
	v_writelane_b32 v252, s5, 7
	s_branch .Lsl9_22

.Lsl9_out:
	s_cmp_gt_i32 s88, 9
	s_cbranch_scc1 .Lsb9_skip
	s_cmp_lt_i32 s89, 11
	s_cbranch_scc1 .Lsb9_skip
	s_waitcnt vmcnt(0) lgkmcnt(0)
	s_and_saveexec_b64 s[16:17], s[92:93]
	s_cbranch_execz .Lsb9_done
	v_mov_b32_e32 v0, 0x24008
	ds_read_b32 v1, v0
	buffer_inv sc1
	s_add_u32 s18, s34, 0xed10500
	s_addc_u32 s19, s35, 0
	v_mov_b32_e32 v0, 0
	s_mov_b32 s20, 0
	s_waitcnt lgkmcnt(0)

.Lsb9_skip:
	s_cmp_gt_i32 s89, 10
	s_cselect_b64 s[8:9], -1, 0
	s_waitcnt lgkmcnt(0)
	s_cmp_lt_i32 s88, 11
	s_cselect_b64 s[4:5], -1, 0
	s_and_b64 s[6:7], s[4:5], s[8:9]
	s_andn2_b64 vcc, exec, s[6:7]
	s_cbranch_vccnz .LBB0_1211
	s_cmpk_gt_i32 s2, 0xff
	s_cbranch_scc1 .LBB0_1211
	s_add_u32 s14, s34, 0x28c4000
	s_addc_u32 s15, s35, 0
	s_add_u32 s33, s34, 0x1da0000
	s_waitcnt lgkmcnt(0)
	s_addc_u32 s56, s35, 0
	s_lshl_b32 s6, s2, 5
	s_and_b32 s6, s6, 0xe0
	s_ashr_i32 s7, s2, 3
	s_add_i32 s6, s6, s7
	s_ashr_i32 s72, s6, 7
	s_lshl_b32 s6, s6, 6
	s_and_b32 s74, s6, 0x1f00
	s_lshl_b32 s6, s7, 8
	v_mov_b32_e32 v76, v204
	s_and_b32 s73, s6, 0x300
	s_mul_i32 s6, s74, 0x1600
	s_add_u32 s6, s14, s6
	v_ashrrev_i32_e32 v77, 3, v76
	s_waitcnt vmcnt(7)
	v_lshlrev_b32_e32 v0, 3, v76
	s_movk_i32 s8, 0xb00
	v_and_b32_e32 v78, 56, v0
	s_addc_u32 s7, s15, 0
	s_mul_i32 s10, s72, 0xb00
	v_mul_lo_u32 v0, v77, s8
	s_mul_hi_i32 s9, s72, 0xb00
	s_add_u32 s52, s6, s10
	v_or_b32_e32 v0, v0, v78
	v_mov_b32_e32 v199, 0
	s_addc_u32 s53, s7, s9
	v_lshlrev_b32_e32 v196, 1, v0
	v_mov_b32_e32 v197, v199
	v_lshl_add_u64 v[0:1], s[52:53], 0, v[196:197]
	s_mov_b32 s57, 0x58000
	s_mul_i32 s6, s73, 0x1600
	v_add_co_u32_e32 v64, vcc, s57, v0
	s_add_u32 s6, s33, s6
	s_nop 0
	v_addc_co_u32_e32 v65, vcc, 0, v1, vcc
	s_mov_b32 s58, 0xb0000
	s_addc_u32 s7, s56, 0
	v_add_co_u32_e32 v66, vcc, s58, v0
	s_add_u32 s54, s6, s10
	s_nop 0
	v_addc_co_u32_e32 v67, vcc, 0, v1, vcc
	s_mov_b32 s59, 0x108000
	s_addc_u32 s55, s7, s9
	global_load_dwordx4 v[32:35], v196, s[52:53]
	global_load_dwordx4 v[48:51], v196, s[54:55]
	v_add_co_u32_e32 v68, vcc, s59, v0
	global_load_dwordx4 v[36:39], v[64:65], off
	global_load_dwordx4 v[40:43], v[66:67], off
	v_addc_co_u32_e32 v69, vcc, 0, v1, vcc
	v_lshl_add_u64 v[0:1], s[54:55], 0, v[196:197]
	v_add_co_u32_e32 v70, vcc, s57, v0
	global_load_dwordx4 v[44:47], v[68:69], off
	s_nop 0
	v_addc_co_u32_e32 v71, vcc, 0, v1, vcc
	v_add_co_u32_e32 v72, vcc, s58, v0
	global_load_dwordx4 v[52:55], v[70:71], off
	s_nop 0
	v_addc_co_u32_e32 v73, vcc, 0, v1, vcc
	global_load_dwordx4 v[56:59], v[72:73], off
	v_add_co_u32_e32 v74, vcc, s59, v0
	s_movk_i32 s6, 0x90
	s_nop 0
	v_addc_co_u32_e32 v75, vcc, 0, v1, vcc
	global_load_dwordx4 v[60:63], v[74:75], off
	global_load_dwordx4 v[4:7], v196, s[52:53] offset:128
	global_load_dwordx4 v[8:11], v[64:65], off offset:128
	global_load_dwordx4 v[12:15], v[66:67], off offset:128
	global_load_dwordx4 v[16:19], v[68:69], off offset:128
	global_load_dwordx4 v[0:3], v196, s[54:55] offset:128
	global_load_dwordx4 v[20:23], v[70:71], off offset:128
	global_load_dwordx4 v[24:27], v[72:73], off offset:128
	global_load_dwordx4 v[28:31], v[74:75], off offset:128
	v_ashrrev_i32_e32 v65, 1, v76
	v_mul_lo_u32 v66, v77, s6
	v_bfe_u32 v64, v76, 4, 2
	v_and_b32_e32 v65, 0xffffff80, v65
	v_lshl_add_u32 v202, v78, 1, v66
	v_lshrrev_b32_e32 v158, 3, v76
	v_lshrrev_b32_e32 v159, 1, v158
	v_xor_b32_e32 v158, v158, v159
	v_bfe_u32 v158, v158, 2, 1
	v_and_b32_e32 v159, v158, v76
	v_lshlrev_b32_e32 v159, 5, v159
	v_lshlrev_b32_e32 v158, 4, v158
	v_sub_u32_e32 v158, v158, v159
	v_add_u32_e32 v202, v202, v158
	v_add_u32_e32 v206, 0x12000, v202
	v_and_b32_e32 v207, 0xcf, v76
	v_lshl_or_b32 v203, v64, 2, v65
	v_add_u32_e32 v208, 0x1b000, v202
	s_mov_b32 s60, 0x20000
	s_mov_b64 s[8:9], 0x20800
	s_mov_b64 s[10:11], 0x21000
	s_mov_b32 s61, 0x21000
	s_mov_b64 s[12:13], 0x21800
	s_mov_b64 s[16:17], 0x28000
	s_mov_b32 s62, 0x28000
	s_mov_b64 s[18:19], 0x28800
	s_mov_b64 s[20:21], 0x29000
	s_mov_b32 s63, 0x29000
	s_mov_b64 s[22:23], 0x29800
	s_mov_b64 s[24:25], 0x30000
	s_mov_b32 s64, 0x30000
	s_mov_b64 s[26:27], 0x30800
	s_mov_b64 s[28:29], 0x31000
	s_waitcnt vmcnt(15)
	ds_write_b128 v202, v[32:35]
	s_waitcnt vmcnt(13)
	ds_write_b128 v202, v[36:39] offset:9216
	s_waitcnt vmcnt(12)
	ds_write_b128 v202, v[40:43] offset:18432
	s_waitcnt vmcnt(11)
	ds_write_b128 v202, v[44:47] offset:27648
	ds_write_b128 v206, v[48:51]
	s_waitcnt vmcnt(10)
	ds_write_b128 v206, v[52:55] offset:9216
	s_waitcnt vmcnt(9)
	ds_write_b128 v206, v[56:59] offset:18432
	s_waitcnt vmcnt(8)
	ds_write_b128 v206, v[60:63] offset:27648
	v_and_or_b32 v33, v76, 15, v65
	v_lshlrev_b32_e32 v32, 4, v64
	v_lshrrev_b32_e32 v159, 1, v76
	v_xor_b32_e32 v158, v76, v159
	v_bfe_u32 v158, v158, 2, 1
	v_bfe_u32 v159, v76, 4, 1
	v_and_b32_e32 v159, v159, v158
	v_lshlrev_b32_e32 v159, 5, v159
	v_lshlrev_b32_e32 v158, 4, v158
	v_sub_u32_e32 v158, v158, v159
	v_add_u32_e32 v32, v32, v158
	v_mad_u64_u32 v[200:201], s[6:7], v33, s6, v[32:33]
	v_mul_u32_u24_e32 v33, 0x48, v207
	v_lshl_add_u32 v32, v33, 1, v32
	v_add_u32_e32 v201, 0x12000, v32
	v_add_u32_e32 v209, 0x1b000, v32
	s_mov_b64 s[6:7], 0x20000
	s_mov_b32 s65, 0x31000
	s_mov_b64 s[30:31], 0x31800
	s_mov_b64 s[36:37], 0x38000
	s_mov_b32 s66, 0x38000
	s_mov_b64 s[38:39], 0x38800
	s_mov_b64 s[40:41], 0x39000
	s_mov_b32 s67, 0x39000
	s_mov_b64 s[42:43], 0x39800
	s_mov_b32 s68, s2
	s_mov_b64 s[44:45], s[52:53]
	s_mov_b64 s[48:49], s[54:55]
	s_waitcnt lgkmcnt(0)
	s_barrier
